# selected-branch loop: one-dword-per-line touch loads for the next tile's K and V lines issued a full tile ahead (software prefetch into L1/L2), waits recounted
# baseline (speedup 1.0000x reference)
.LBB0_625:
	v_mov_b32_e32 v0, 0x1400000
	s_add_i32 s82, s18, s16
	v_mad_i64_i32 v[2:3], s[4:5], s16, v0, v[154:155]
	s_ashr_i32 s83, s82, 31
	s_lshl_b32 s74, s24, 7
	s_lshl_b64 s[4:5], s[82:83], 19
	s_waitcnt lgkmcnt(0)
	v_lshl_add_u64 v[148:149], v[2:3], 0, s[74:75]
	v_lshl_add_u64 v[2:3], v[164:165], 0, s[4:5]
	s_lshl_b64 s[4:5], 2, s17
	ds_read_b64 v[152:153], v37 offset:18432
	s_waitcnt lgkmcnt(0)
	s_add_u32 s4, s4, -1
	v_and_b32_e32 v8, 31, v195
	v_ashrrev_i32_e32 v9, 5, v195
	s_addc_u32 s5, s5, -1
	v_mul_u32_u24_e32 v0, 0xa00, v8
	v_lshlrev_b32_e32 v6, 3, v9
	s_and_b64 s[94:95], s[20:21], s[4:5]
	v_lshlrev_b32_e32 v0, 1, v0
	v_ashrrev_i32_e32 v7, 31, v6
	v_lshl_add_u64 v[4:5], v[148:149], 0, v[0:1]
	v_lshlrev_b64 v[6:7], 1, v[6:7]
	s_ff1_i32_b64 s4, s[94:95]
	v_lshl_add_u64 v[180:181], v[4:5], 0, v[6:7]
	v_lshl_add_u64 v[2:3], v[2:3], 0, v[6:7]
	v_lshlrev_b32_e32 v0, 5, v8
	v_mov_b32_e32 v14, v1
	v_mov_b32_e32 v15, v1
	v_lshl_add_u64 v[182:183], v[2:3], 0, v[0:1]
	s_mov_b64 s[100:101], 0x1400000
	s_mov_b32 s99, 0
	v_lshl_add_u64 v[240:241], v[182:183], 0, s[100:101]
	v_lshlrev_b32_e32 v230, 6, v195
	v_and_b32_e32 v231, 31, v195
	v_lshlrev_b32_e32 v231, 5, v231
	v_sub_u32_e32 v230, v230, v231
	v_lshrrev_b32_e32 v231, 5, v195
	v_lshlrev_b32_e32 v231, 4, v231
	v_sub_u32_e32 v230, v230, v231
	v_mov_b32_e32 v231, 0
	v_lshl_add_u64 v[224:225], v[182:183], 0, v[230:231]
	v_lshl_add_u64 v[228:229], v[240:241], 0, v[230:231]
	s_mov_b32 s101, 0
	s_lshl_b32 s74, s4, 13
	v_lshl_add_u64 v[4:5], v[240:241], 0, s[74:75]
	global_load_dwordx4 v[118:121], v[4:5], off
	global_load_dwordx4 v[122:125], v[4:5], off offset:1024
	global_load_dwordx4 v[126:129], v[4:5], off offset:2048
	global_load_dwordx4 v[114:117], v[4:5], off offset:3072
	v_lshlrev_b32_e32 v173, 2, v9
	v_mov_b32_e32 v0, v1
	v_mov_b32_e32 v2, v1
	v_mov_b32_e32 v3, v1
	v_mov_b32_e32 v4, v1
	v_mov_b32_e32 v5, v1
	v_mov_b32_e32 v6, v1
	v_mov_b32_e32 v7, v1
	v_mov_b32_e32 v8, v1
	v_mov_b32_e32 v9, v1
	v_mov_b32_e32 v10, v1
	v_mov_b32_e32 v11, v1
	v_mov_b32_e32 v12, v1
	v_mov_b32_e32 v13, v1
	v_mov_b64_e32 v[64:65], v[14:15]
	v_mov_b64_e32 v[48:49], v[14:15]
	v_mov_b64_e32 v[32:33], v[14:15]
	v_mov_b32_e32 v151, 0
	v_mov_b64_e32 v[62:63], v[12:13]
	v_mov_b64_e32 v[60:61], v[10:11]
	v_mov_b64_e32 v[58:59], v[8:9]
	v_mov_b64_e32 v[56:57], v[6:7]
	v_mov_b64_e32 v[54:55], v[4:5]
	v_mov_b64_e32 v[52:53], v[2:3]
	v_mov_b64_e32 v[50:51], v[0:1]
	v_mov_b64_e32 v[46:47], v[12:13]
	v_mov_b64_e32 v[44:45], v[10:11]
	v_mov_b64_e32 v[42:43], v[8:9]
	v_mov_b64_e32 v[40:41], v[6:7]
	v_mov_b64_e32 v[38:39], v[4:5]
	v_mov_b64_e32 v[36:37], v[2:3]
	v_mov_b64_e32 v[34:35], v[0:1]
	v_mov_b64_e32 v[30:31], v[12:13]
	v_mov_b64_e32 v[28:29], v[10:11]
	v_mov_b64_e32 v[26:27], v[8:9]
	v_mov_b64_e32 v[24:25], v[6:7]
	v_mov_b64_e32 v[22:23], v[4:5]
	v_mov_b64_e32 v[20:21], v[2:3]
	v_mov_b64_e32 v[18:19], v[0:1]
	v_mov_b64_e32 v[16:17], v[14:15]
	v_add_u32_e32 v175, 6, v172
	v_add_u32_e32 v184, 5, v172
	s_mov_b32 s8, 0
	v_mov_b32_e32 v203, 0xf149f2ca
	v_mov_b32_e32 v150, v151
	v_mov_b32_e32 v185, 0xf149f2ca
	v_mov_b64_e32 v[14:15], v[12:13]
	v_mov_b64_e32 v[12:13], v[10:11]
	v_mov_b64_e32 v[10:11], v[8:9]
	v_mov_b64_e32 v[8:9], v[6:7]
	v_mov_b64_e32 v[6:7], v[4:5]
	v_mov_b64_e32 v[4:5], v[2:3]
	v_mov_b64_e32 v[2:3], v[0:1]
	s_mov_b32 s83, s4

.LBB0_630:
	s_lshl_b32 s74, s9, 7
	v_lshl_add_u64 v[66:67], v[182:183], 0, s[74:75]
	global_load_dwordx4 v[142:145], v[66:67], off
	global_load_dwordx4 v[138:141], v[66:67], off offset:2048
	global_load_dwordx4 v[134:137], v[66:67], off offset:1024
	global_load_dwordx4 v[130:133], v[66:67], off offset:3072
	s_lshl_b32 s100, s90, 5
	s_add_i32 s100, s100, s91
	s_lshl_b32 s100, s100, 7
	v_lshl_add_u64 v[226:227], v[224:225], 0, s[100:101]
	global_load_dword v233, v[226:227], off
	v_lshl_add_u64 v[226:227], v[228:229], 0, s[100:101]
	global_load_dword v233, v[226:227], off
	s_cmp_eq_u64 s[6:7], 0
	s_cbranch_scc1 .Lsel_skip0
.Lsel_noskip0:
	s_waitcnt vmcnt(6)
	v_mfma_f32_32x32x16_bf16 v[66:81], v[118:121], v[82:85], 0
	v_mfma_f32_32x32x16_bf16 v[66:81], v[122:125], v[86:89], v[66:81]
	v_mfma_f32_32x32x16_bf16 v[66:81], v[126:129], v[90:93], v[66:81]
	v_mfma_f32_32x32x16_bf16 v[66:81], v[114:117], v[94:97], v[66:81]
	s_and_b64 vcc, exec, s[56:57]
	s_cbranch_vccnz .LBB0_632
	v_add_u32_e32 v186, s9, v173
	v_or_b32_e32 v202, 2, v186
	v_or_b32_e32 v200, 3, v186
	v_add_u32_e32 v192, 8, v186
	v_add_u32_e32 v201, 9, v186
	v_add_u32_e32 v193, 10, v186
	v_add_u32_e32 v191, 11, v186
	v_add_u32_e32 v190, 16, v186
	v_add_u32_e32 v189, 17, v186
	v_add_u32_e32 v188, 18, v186
	v_add_u32_e32 v187, 19, v186
	v_cmp_le_i32_e64 s[10:11], v186, v172
	v_cmp_lt_i32_e64 s[8:9], v186, v172
	v_cmp_le_i32_e64 s[30:31], v202, v172
	v_cmp_le_i32_e64 s[28:29], v200, v172
	v_cmp_le_i32_e64 s[26:27], v192, v172
	v_cmp_le_i32_e64 s[22:23], v201, v172
	v_cmp_le_i32_e64 s[18:19], v193, v172
	v_cmp_le_i32_e64 s[14:15], v191, v172
	v_cmp_le_i32_e64 s[12:13], v190, v172
	v_cmp_le_i32_e64 s[24:25], v189, v172
	v_cmp_le_i32_e64 s[20:21], v188, v172
	v_cmp_le_i32_e64 s[16:17], v187, v172
	s_and_b64 vcc, s[6:7], s[10:11]
	s_nop 6
	v_cndmask_b32_e32 v66, v248, v66, vcc
	s_and_b64 vcc, s[6:7], s[8:9]
	v_cndmask_b32_e32 v67, v248, v67, vcc
	s_and_b64 vcc, s[6:7], s[30:31]
	v_cndmask_b32_e32 v68, v248, v68, vcc
	s_and_b64 vcc, s[6:7], s[28:29]
	v_cndmask_b32_e32 v69, v248, v69, vcc
	s_and_b64 vcc, s[6:7], s[26:27]
	v_cndmask_b32_e32 v70, v248, v70, vcc
	s_and_b64 vcc, s[6:7], s[22:23]
	v_cndmask_b32_e32 v71, v248, v71, vcc
	s_and_b64 vcc, s[6:7], s[18:19]
	v_cndmask_b32_e32 v72, v248, v72, vcc
	s_and_b64 vcc, s[6:7], s[14:15]
	v_cndmask_b32_e32 v73, v248, v73, vcc
	s_and_b64 vcc, s[6:7], s[12:13]
	v_cndmask_b32_e32 v74, v248, v74, vcc
	s_and_b64 vcc, s[6:7], s[24:25]
	v_cndmask_b32_e32 v75, v248, v75, vcc
	s_and_b64 vcc, s[6:7], s[20:21]
	v_cndmask_b32_e32 v76, v248, v76, vcc
	s_and_b64 vcc, s[6:7], s[16:17]
	v_add_u32_e32 v0, 24, v186
	v_cndmask_b32_e32 v77, v248, v77, vcc
	v_cmp_le_i32_e32 vcc, v0, v172
	s_and_b64 vcc, s[6:7], vcc
	v_add_u32_e32 v0, 25, v186
	v_cndmask_b32_e32 v78, v248, v78, vcc
	v_cmp_le_i32_e32 vcc, v0, v172
	s_and_b64 vcc, s[6:7], vcc
	v_add_u32_e32 v0, 26, v186
	v_cndmask_b32_e32 v79, v248, v79, vcc
	v_cmp_le_i32_e32 vcc, v0, v172
	s_and_b64 vcc, s[6:7], vcc
	v_add_u32_e32 v0, 27, v186
	v_cndmask_b32_e32 v80, v248, v80, vcc
	v_cmp_le_i32_e32 vcc, v0, v172
	s_and_b64 vcc, s[6:7], vcc
	s_nop 0
	v_cndmask_b32_e32 v81, v248, v81, vcc

.Lsel_join0:
	v_add_f32_e32 v151, v151, v196
	v_cvt_pk_bf16_f32 v66, v204, v205
	v_cvt_pk_bf16_f32 v67, v206, v207
	v_cvt_pk_bf16_f32 v68, v208, v209
	v_cvt_pk_bf16_f32 v69, v210, v211
	v_cvt_pk_bf16_f32 v70, v212, v213
	v_cvt_pk_bf16_f32 v71, v214, v215
	v_cvt_pk_bf16_f32 v72, v216, v217
	v_cvt_pk_bf16_f32 v73, v218, v219
	s_waitcnt vmcnt(2) lgkmcnt(0)
	v_mfma_f32_32x32x16_bf16 v[50:65], v[142:145], v[66:69], v[50:65]
	s_lshl_b32 s8, s90, 5
	s_add_i32 s8, s8, s91
	s_lshl_b32 s98, s8, 7
	v_lshl_add_u64 v[220:221], v[240:241], 0, s[98:99]
	s_xor_b64 s[6:7], s[56:57], -1
	v_mfma_f32_32x32x16_bf16 v[34:49], v[134:137], v[66:69], v[34:49]
	s_andn2_b64 vcc, exec, s[6:7]
	v_mfma_f32_32x32x16_bf16 v[50:65], v[138:141], v[70:73], v[50:65]
	v_mfma_f32_32x32x16_bf16 v[34:49], v[130:133], v[70:73], v[34:49]
	s_cmp_eq_u64 s[4:5], 0
	s_cbranch_scc1 .Lsel_skip1
	v_mfma_f32_32x32x16_bf16 v[66:81], v[118:121], v[98:101], 0
	v_mfma_f32_32x32x16_bf16 v[66:81], v[122:125], v[102:105], v[66:81]
	v_mfma_f32_32x32x16_bf16 v[66:81], v[126:129], v[106:109], v[66:81]
	v_mfma_f32_32x32x16_bf16 v[66:81], v[114:117], v[110:113], v[66:81]
	global_load_dwordx4 v[118:121], v[220:221], off
	global_load_dwordx4 v[122:125], v[220:221], off offset:1024
	global_load_dwordx4 v[126:129], v[220:221], off offset:2048
	global_load_dwordx4 v[114:117], v[220:221], off offset:3072
	s_cbranch_vccnz .LBB0_637
	v_cmp_le_i32_e32 vcc, v186, v174
	s_and_b64 vcc, s[4:5], vcc
	s_nop 4
	v_cndmask_b32_e32 v66, v248, v66, vcc
	v_cmp_lt_i32_e32 vcc, v186, v174
	s_and_b64 vcc, s[4:5], vcc
	s_nop 0
	v_cndmask_b32_e32 v67, v248, v67, vcc
	v_cmp_le_i32_e32 vcc, v186, v175
	s_and_b64 vcc, s[4:5], vcc
	s_nop 0
	v_cndmask_b32_e32 v68, v248, v68, vcc
	v_cmp_le_i32_e32 vcc, v186, v184
	s_and_b64 vcc, s[4:5], vcc
	s_nop 0
	v_cndmask_b32_e32 v69, v248, v69, vcc
	v_cmp_le_i32_e32 vcc, v186, v172
	s_and_b64 vcc, s[4:5], vcc
	s_nop 0
	v_cndmask_b32_e32 v70, v248, v70, vcc
	v_cmp_lt_i32_e32 vcc, v186, v172
	s_and_b64 vcc, s[4:5], vcc
	s_nop 0
	v_cndmask_b32_e32 v71, v248, v71, vcc
	v_cmp_le_i32_e32 vcc, v202, v172
	s_and_b64 vcc, s[4:5], vcc
	s_nop 0
	v_cndmask_b32_e32 v72, v248, v72, vcc
	v_cmp_le_i32_e32 vcc, v200, v172
	s_and_b64 vcc, s[4:5], vcc
	s_nop 0
	v_cndmask_b32_e32 v73, v248, v73, vcc
	v_cmp_le_i32_e32 vcc, v192, v172
	s_and_b64 vcc, s[4:5], vcc
	s_nop 0
	v_cndmask_b32_e32 v74, v248, v74, vcc
	v_cmp_le_i32_e32 vcc, v201, v172
	s_and_b64 vcc, s[4:5], vcc
	s_nop 0
	v_cndmask_b32_e32 v75, v248, v75, vcc
	v_cmp_le_i32_e32 vcc, v193, v172
	s_and_b64 vcc, s[4:5], vcc
	s_nop 0
	v_cndmask_b32_e32 v76, v248, v76, vcc
	v_cmp_le_i32_e32 vcc, v191, v172
	s_and_b64 vcc, s[4:5], vcc
	s_nop 0
	v_cndmask_b32_e32 v77, v248, v77, vcc
	v_cmp_le_i32_e32 vcc, v190, v172
	s_and_b64 vcc, s[4:5], vcc
	s_nop 0
	v_cndmask_b32_e32 v78, v248, v78, vcc
	v_cmp_le_i32_e32 vcc, v189, v172
	s_and_b64 vcc, s[4:5], vcc
	s_nop 0
	v_cndmask_b32_e32 v79, v248, v79, vcc
	v_cmp_le_i32_e32 vcc, v188, v172
	s_and_b64 vcc, s[4:5], vcc
	s_nop 0
	v_cndmask_b32_e32 v80, v248, v80, vcc
	v_cmp_le_i32_e32 vcc, v187, v172
	s_and_b64 vcc, s[4:5], vcc
	s_nop 0
	v_cndmask_b32_e32 v81, v248, v81, vcc

.Lsel_join1:
	v_add_f32_e32 v150, v150, v186
	v_cvt_pk_bf16_f32 v66, v204, v205
	v_cvt_pk_bf16_f32 v67, v206, v207
	v_cvt_pk_bf16_f32 v68, v208, v209
	v_cvt_pk_bf16_f32 v69, v210, v211
	v_cvt_pk_bf16_f32 v70, v212, v213
	v_cvt_pk_bf16_f32 v71, v214, v215
	v_cvt_pk_bf16_f32 v72, v216, v217
	v_cvt_pk_bf16_f32 v73, v218, v219
	s_waitcnt vmcnt(6)
	v_mfma_f32_32x32x16_bf16 v[18:33], v[142:145], v[66:69], v[18:33]
	v_mfma_f32_32x32x16_bf16 v[2:17], v[134:137], v[66:69], v[2:17]
	v_mfma_f32_32x32x16_bf16 v[18:33], v[138:141], v[70:73], v[18:33]
	v_mfma_f32_32x32x16_bf16 v[2:17], v[130:133], v[70:73], v[2:17]

.Lsel_skip0:
	s_and_b64 vcc, exec, s[56:57]
	s_cbranch_vccz .Lsel_noskip0
	s_lshl_b32 s8, s90, 5
	s_add_i32 s8, s8, s91
	s_lshl_b32 s98, s8, 7
	v_lshl_add_u64 v[220:221], v[240:241], 0, s[98:99]
	s_mov_b64 s[6:7], 0
	s_waitcnt vmcnt(6)
	v_mfma_f32_32x32x16_bf16 v[66:81], v[118:121], v[98:101], 0
	v_mfma_f32_32x32x16_bf16 v[66:81], v[122:125], v[102:105], v[66:81]
	v_mfma_f32_32x32x16_bf16 v[66:81], v[126:129], v[106:109], v[66:81]
	v_mfma_f32_32x32x16_bf16 v[66:81], v[114:117], v[110:113], v[66:81]
	global_load_dwordx4 v[118:121], v[220:221], off
	global_load_dwordx4 v[122:125], v[220:221], off offset:1024
	global_load_dwordx4 v[126:129], v[220:221], off offset:2048
	global_load_dwordx4 v[114:117], v[220:221], off offset:3072
	s_branch .LBB0_637
